# sample-row normalise/store moved ahead of the y stores (speculative counter+yss loads)
# baseline (speedup 1.0000x reference)
.LBB0_530:
	v_lshl_add_u64 v[130:131], v[130:131], 2, s[10:11]
	global_load_dword v182, v[130:131], off sc1
	global_load_dword v183, v[130:131], off offset:64 sc1
	global_load_dword v184, v[130:131], off offset:128 sc1
	global_load_dword v185, v[130:131], off offset:192 sc1
	global_load_dword v186, v[130:131], off offset:512 sc1
	global_load_dword v187, v[130:131], off offset:576 sc1
	global_load_dword v188, v[130:131], off offset:640 sc1
	global_load_dword v189, v[130:131], off offset:704 sc1
	v_mov_b32_e32 v178, 0x3727c5ac
	v_lshl_add_u64 v[132:133], s[66:67], 0, v[132:133]
	v_lshlrev_b64 v[128:129], 2, v[128:129]
	v_lshl_add_u64 v[132:133], v[132:133], 0, v[128:129]
	v_lshl_add_u64 v[136:137], v[136:137], 2, s[10:11]
	s_bfe_u32 s0, s79, 0x20006
	s_cmp_lg_u32 s0, 0
	s_cbranch_scc1 .Ls3a_done
	s_lshl_b32 s0, s72, 8
	s_add_u32 s0, s68, s0
	s_addc_u32 s1, s69, 0
	v_mov_b32_e32 v202, 0x48000
	v_add_u32_e32 v203, 0x20400, v252
	global_load_dword v207, v202, s[0:1] sc1
	global_load_dword v206, v203, s[68:69] sc1
.Ls3a_done:
	s_waitcnt vmcnt(0)
	v_mov_b32_e32 v170, v182
	s_bfe_u32 s80, s79, 0x20006
	s_cmp_lg_u32 s80, 0
	s_cbranch_scc1 .Ls3_done
	v_readfirstlane_b32 s80, v207
	s_nop 3
	s_cmp_ge_u32 s80, 64
	s_cbranch_scc1 .Ls3_go
	s_mov_b32 s3, 0x100000
.Ls3_spin:
	global_load_dword v207, v202, s[0:1] sc1
	s_waitcnt vmcnt(0)
	v_readfirstlane_b32 s80, v207
	s_nop 3
	s_cmp_ge_u32 s80, 64
	s_cbranch_scc1 .Ls3_reload
	s_sleep 1
	s_sub_u32 s3, s3, 1
	s_cmp_eq_u32 s3, 0
	s_cbranch_scc0 .Ls3_spin
.Ls3_reload:
	global_load_dword v206, v203, s[68:69] sc1
	s_waitcnt vmcnt(0)
.Ls3_go:
	v_mov_b32_e32 v208, 0x3727c5ac
	v_mov_b32_e32 v202, v250
	v_mov_b32_e32 v203, 0
	v_mov_b32_e32 v204, v251
	v_mov_b32_e32 v205, 0
	v_lshl_add_u64 v[202:203], s[66:67], 0, v[202:203]
	v_lshl_add_u64 v[202:203], v[204:205], 2, v[202:203]
	v_add_co_u32_e32 v202, vcc, 0x4000000, v202
	v_fmac_f32_e32 v208, 0x3a800000, v206
	v_rsq_f32_e32 v206, v208
	v_addc_co_u32_e32 v203, vcc, 0, v203, vcc
	v_pk_mul_f32 v[248:249], v[248:249], v[206:207] op_sel_hi:[1,0]
	v_pk_mul_f32 v[246:247], v[246:247], v[206:207] op_sel_hi:[1,0]
	v_pk_mul_f32 v[242:243], v[242:243], v[248:249]
	v_pk_mul_f32 v[244:245], v[244:245], v[246:247]
	global_store_dwordx4 v[202:203], v[242:245], off
.Ls3_done:
	v_fmamk_f32 v170, v170, 0x3a800000, v178
	v_rsq_f32_e32 v170, v170
	s_nop 0
	v_pk_mul_f32 v[124:125], v[124:125], v[170:171] op_sel_hi:[1,0]
	v_pk_mul_f32 v[126:127], v[126:127], v[170:171] op_sel_hi:[1,0]
	v_pk_mul_f32 v[120:121], v[120:121], v[170:171] op_sel_hi:[1,0]
	v_pk_mul_f32 v[122:123], v[122:123], v[170:171] op_sel_hi:[1,0]
	v_pk_mul_f32 v[172:173], v[116:117], v[170:171] op_sel_hi:[1,0]
	v_pk_mul_f32 v[174:175], v[118:119], v[170:171] op_sel_hi:[1,0]
	v_pk_mul_f32 v[176:177], v[112:113], v[170:171] op_sel_hi:[1,0]
	v_pk_mul_f32 v[170:171], v[114:115], v[170:171] op_sel_hi:[1,0]
	v_pk_mul_f32 v[114:115], v[14:15], v[126:127]
	v_pk_mul_f32 v[112:113], v[12:13], v[124:125]
	v_pk_mul_f32 v[118:119], v[10:11], v[122:123]
	v_pk_mul_f32 v[116:117], v[8:9], v[120:121]
	v_pk_mul_f32 v[122:123], v[6:7], v[174:175]
	v_pk_mul_f32 v[120:121], v[4:5], v[172:173]
	v_pk_mul_f32 v[126:127], v[2:3], v[170:171]
	v_pk_mul_f32 v[124:125], v[0:1], v[176:177]
	global_store_dwordx4 v[132:133], v[112:115], off
	global_store_dwordx4 v[132:133], v[116:119], off offset:64
	global_store_dwordx4 v[132:133], v[120:123], off offset:512
	global_store_dwordx4 v[132:133], v[124:127], off offset:576
	v_mov_b32_e32 v112, v183
	v_lshl_add_u64 v[114:115], s[66:67], 0, v[134:135]
	v_lshl_add_u64 v[114:115], v[114:115], 0, v[128:129]
	v_lshl_add_u64 v[116:117], v[140:141], 2, s[10:11]
	v_fmamk_f32 v112, v112, 0x3a800000, v178
	v_rsq_f32_e32 v112, v112
	s_nop 0
	v_pk_mul_f32 v[108:109], v[108:109], v[112:113] op_sel_hi:[1,0]
	v_pk_mul_f32 v[110:111], v[110:111], v[112:113] op_sel_hi:[1,0]
	v_pk_mul_f32 v[104:105], v[104:105], v[112:113] op_sel_hi:[1,0]
	v_pk_mul_f32 v[106:107], v[106:107], v[112:113] op_sel_hi:[1,0]
	v_pk_mul_f32 v[118:119], v[100:101], v[112:113] op_sel_hi:[1,0]
	v_pk_mul_f32 v[120:121], v[102:103], v[112:113] op_sel_hi:[1,0]
	v_pk_mul_f32 v[122:123], v[96:97], v[112:113] op_sel_hi:[1,0]
	v_pk_mul_f32 v[112:113], v[98:99], v[112:113] op_sel_hi:[1,0]
	v_pk_mul_f32 v[98:99], v[14:15], v[110:111]
	v_pk_mul_f32 v[96:97], v[12:13], v[108:109]
	v_pk_mul_f32 v[102:103], v[10:11], v[106:107]
	v_pk_mul_f32 v[100:101], v[8:9], v[104:105]
	v_pk_mul_f32 v[106:107], v[6:7], v[120:121]
	v_pk_mul_f32 v[104:105], v[4:5], v[118:119]
	v_pk_mul_f32 v[110:111], v[2:3], v[112:113]
	v_pk_mul_f32 v[108:109], v[0:1], v[122:123]
	global_store_dwordx4 v[114:115], v[96:99], off
	global_store_dwordx4 v[114:115], v[100:103], off offset:64
	global_store_dwordx4 v[114:115], v[104:107], off offset:512
	global_store_dwordx4 v[114:115], v[108:111], off offset:576
	v_mov_b32_e32 v96, v184
	v_lshl_add_u64 v[98:99], s[66:67], 0, v[138:139]
	v_lshl_add_u64 v[98:99], v[98:99], 0, v[128:129]
	v_lshl_add_u64 v[100:101], v[144:145], 2, s[10:11]
	v_fmamk_f32 v96, v96, 0x3a800000, v178
	v_rsq_f32_e32 v96, v96
	s_nop 0
	v_pk_mul_f32 v[92:93], v[92:93], v[96:97] op_sel_hi:[1,0]
	v_pk_mul_f32 v[94:95], v[94:95], v[96:97] op_sel_hi:[1,0]
	v_pk_mul_f32 v[88:89], v[88:89], v[96:97] op_sel_hi:[1,0]
	v_pk_mul_f32 v[90:91], v[90:91], v[96:97] op_sel_hi:[1,0]
	v_pk_mul_f32 v[102:103], v[84:85], v[96:97] op_sel_hi:[1,0]
	v_pk_mul_f32 v[104:105], v[86:87], v[96:97] op_sel_hi:[1,0]
	v_pk_mul_f32 v[106:107], v[80:81], v[96:97] op_sel_hi:[1,0]
	v_pk_mul_f32 v[96:97], v[82:83], v[96:97] op_sel_hi:[1,0]
	v_pk_mul_f32 v[82:83], v[14:15], v[94:95]
	v_pk_mul_f32 v[80:81], v[12:13], v[92:93]
	v_pk_mul_f32 v[86:87], v[10:11], v[90:91]
	v_pk_mul_f32 v[84:85], v[8:9], v[88:89]
	v_pk_mul_f32 v[90:91], v[6:7], v[104:105]
	v_pk_mul_f32 v[88:89], v[4:5], v[102:103]
	v_pk_mul_f32 v[94:95], v[2:3], v[96:97]
	v_pk_mul_f32 v[92:93], v[0:1], v[106:107]
	global_store_dwordx4 v[98:99], v[80:83], off
	global_store_dwordx4 v[98:99], v[84:87], off offset:64
	global_store_dwordx4 v[98:99], v[88:91], off offset:512
	global_store_dwordx4 v[98:99], v[92:95], off offset:576
	v_mov_b32_e32 v80, v185
	v_lshl_add_u64 v[82:83], s[66:67], 0, v[142:143]
	v_lshl_add_u64 v[82:83], v[82:83], 0, v[128:129]
	v_fmamk_f32 v80, v80, 0x3a800000, v178
	v_rsq_f32_e32 v80, v80
	s_nop 0
	v_pk_mul_f32 v[84:85], v[146:147], v[80:81] op_sel_hi:[1,0]
	v_pk_mul_f32 v[78:79], v[78:79], v[80:81] op_sel_hi:[1,0]
	v_pk_mul_f32 v[76:77], v[76:77], v[80:81] op_sel_hi:[1,0]
	v_pk_mul_f32 v[74:75], v[74:75], v[80:81] op_sel_hi:[1,0]
	v_pk_mul_f32 v[86:87], v[68:69], v[80:81] op_sel_hi:[1,0]
	v_pk_mul_f32 v[88:89], v[70:71], v[80:81] op_sel_hi:[1,0]
	v_pk_mul_f32 v[90:91], v[64:65], v[80:81] op_sel_hi:[1,0]
	v_pk_mul_f32 v[80:81], v[66:67], v[80:81] op_sel_hi:[1,0]
	v_pk_mul_f32 v[66:67], v[14:15], v[78:79]
	v_pk_mul_f32 v[64:65], v[12:13], v[84:85]
	v_pk_mul_f32 v[70:71], v[10:11], v[74:75]
	v_pk_mul_f32 v[68:69], v[8:9], v[76:77]
	v_pk_mul_f32 v[76:77], v[6:7], v[88:89]
	v_pk_mul_f32 v[74:75], v[4:5], v[86:87]
	v_pk_mul_f32 v[80:81], v[2:3], v[80:81]
	v_pk_mul_f32 v[78:79], v[0:1], v[90:91]
	global_store_dwordx4 v[82:83], v[64:67], off
	global_store_dwordx4 v[82:83], v[68:71], off offset:64
	global_store_dwordx4 v[82:83], v[74:77], off offset:512
	global_store_dwordx4 v[82:83], v[78:81], off offset:576
	v_mov_b32_e32 v64, v186
	v_lshl_add_u64 v[66:67], s[66:67], 0, v[72:73]
	v_lshl_add_u64 v[66:67], v[66:67], 0, v[128:129]
	v_fmamk_f32 v64, v64, 0x3a800000, v178
	v_rsq_f32_e32 v64, v64
	s_nop 0
	v_pk_mul_f32 v[68:69], v[148:149], v[64:65] op_sel_hi:[1,0]
	v_pk_mul_f32 v[62:63], v[62:63], v[64:65] op_sel_hi:[1,0]
	v_pk_mul_f32 v[60:61], v[60:61], v[64:65] op_sel_hi:[1,0]
	v_pk_mul_f32 v[58:59], v[58:59], v[64:65] op_sel_hi:[1,0]
	v_pk_mul_f32 v[70:71], v[52:53], v[64:65] op_sel_hi:[1,0]
	v_pk_mul_f32 v[72:73], v[54:55], v[64:65] op_sel_hi:[1,0]
	v_pk_mul_f32 v[74:75], v[48:49], v[64:65] op_sel_hi:[1,0]
	v_pk_mul_f32 v[64:65], v[50:51], v[64:65] op_sel_hi:[1,0]
	v_pk_mul_f32 v[50:51], v[14:15], v[62:63]
	v_pk_mul_f32 v[48:49], v[12:13], v[68:69]
	v_pk_mul_f32 v[54:55], v[10:11], v[58:59]
	v_pk_mul_f32 v[52:53], v[8:9], v[60:61]
	v_pk_mul_f32 v[60:61], v[6:7], v[72:73]
	v_pk_mul_f32 v[58:59], v[4:5], v[70:71]
	v_pk_mul_f32 v[64:65], v[2:3], v[64:65]
	v_pk_mul_f32 v[62:63], v[0:1], v[74:75]
	global_store_dwordx4 v[66:67], v[48:51], off
	global_store_dwordx4 v[66:67], v[52:55], off offset:64
	global_store_dwordx4 v[66:67], v[58:61], off offset:512
	global_store_dwordx4 v[66:67], v[62:65], off offset:576
	v_mov_b32_e32 v48, v187
	v_lshl_add_u64 v[50:51], s[66:67], 0, v[56:57]
	v_lshl_add_u64 v[50:51], v[50:51], 0, v[128:129]
	v_fmamk_f32 v48, v48, 0x3a800000, v178
	v_rsq_f32_e32 v48, v48
	s_nop 0
	v_pk_mul_f32 v[52:53], v[150:151], v[48:49] op_sel_hi:[1,0]
	v_pk_mul_f32 v[46:47], v[46:47], v[48:49] op_sel_hi:[1,0]
	v_pk_mul_f32 v[44:45], v[44:45], v[48:49] op_sel_hi:[1,0]
	v_pk_mul_f32 v[42:43], v[42:43], v[48:49] op_sel_hi:[1,0]
	v_pk_mul_f32 v[54:55], v[36:37], v[48:49] op_sel_hi:[1,0]
	v_pk_mul_f32 v[56:57], v[38:39], v[48:49] op_sel_hi:[1,0]
	v_pk_mul_f32 v[58:59], v[32:33], v[48:49] op_sel_hi:[1,0]
	v_pk_mul_f32 v[48:49], v[34:35], v[48:49] op_sel_hi:[1,0]
	v_pk_mul_f32 v[34:35], v[14:15], v[46:47]
	v_pk_mul_f32 v[32:33], v[12:13], v[52:53]
	v_pk_mul_f32 v[38:39], v[10:11], v[42:43]
	v_pk_mul_f32 v[36:37], v[8:9], v[44:45]
	v_pk_mul_f32 v[44:45], v[6:7], v[56:57]
	v_pk_mul_f32 v[42:43], v[4:5], v[54:55]
	v_pk_mul_f32 v[48:49], v[2:3], v[48:49]
	v_pk_mul_f32 v[46:47], v[0:1], v[58:59]
	global_store_dwordx4 v[50:51], v[32:35], off
	global_store_dwordx4 v[50:51], v[36:39], off offset:64
	global_store_dwordx4 v[50:51], v[42:45], off offset:512
	global_store_dwordx4 v[50:51], v[46:49], off offset:576
	v_mov_b32_e32 v32, v188
	v_lshl_add_u64 v[34:35], s[66:67], 0, v[40:41]
	v_lshl_add_u64 v[34:35], v[34:35], 0, v[128:129]
	v_fmamk_f32 v32, v32, 0x3a800000, v178
	v_rsq_f32_e32 v32, v32
	s_nop 0
	v_pk_mul_f32 v[36:37], v[152:153], v[32:33] op_sel_hi:[1,0]
	v_pk_mul_f32 v[30:31], v[30:31], v[32:33] op_sel_hi:[1,0]
	v_pk_mul_f32 v[28:29], v[28:29], v[32:33] op_sel_hi:[1,0]
	v_pk_mul_f32 v[26:27], v[26:27], v[32:33] op_sel_hi:[1,0]
	v_pk_mul_f32 v[38:39], v[20:21], v[32:33] op_sel_hi:[1,0]
	v_pk_mul_f32 v[40:41], v[22:23], v[32:33] op_sel_hi:[1,0]
	v_pk_mul_f32 v[42:43], v[16:17], v[32:33] op_sel_hi:[1,0]
	v_pk_mul_f32 v[32:33], v[18:19], v[32:33] op_sel_hi:[1,0]
	v_pk_mul_f32 v[18:19], v[14:15], v[30:31]
	v_pk_mul_f32 v[16:17], v[12:13], v[36:37]
	v_pk_mul_f32 v[22:23], v[10:11], v[26:27]
	v_pk_mul_f32 v[20:21], v[8:9], v[28:29]
	v_pk_mul_f32 v[28:29], v[6:7], v[40:41]
	v_pk_mul_f32 v[26:27], v[4:5], v[38:39]
	v_pk_mul_f32 v[32:33], v[2:3], v[32:33]
	v_pk_mul_f32 v[30:31], v[0:1], v[42:43]
	global_store_dwordx4 v[34:35], v[16:19], off
	global_store_dwordx4 v[34:35], v[20:23], off offset:64
	global_store_dwordx4 v[34:35], v[26:29], off offset:512
	global_store_dwordx4 v[34:35], v[30:33], off offset:576
	v_mov_b32_e32 v16, v189
	v_lshl_add_u64 v[18:19], s[66:67], 0, v[24:25]
	v_lshl_add_u64 v[18:19], v[18:19], 0, v[128:129]
	v_fmac_f32_e32 v178, 0x3a800000, v16
	v_rsq_f32_e32 v16, v178
	s_nop 0
	v_pk_mul_f32 v[20:21], v[168:169], v[16:17] op_sel_hi:[1,0]
	v_pk_mul_f32 v[22:23], v[166:167], v[16:17] op_sel_hi:[1,0]
	v_pk_mul_f32 v[24:25], v[164:165], v[16:17] op_sel_hi:[1,0]
	v_pk_mul_f32 v[26:27], v[162:163], v[16:17] op_sel_hi:[1,0]
	v_pk_mul_f32 v[28:29], v[160:161], v[16:17] op_sel_hi:[1,0]
	v_pk_mul_f32 v[30:31], v[158:159], v[16:17] op_sel_hi:[1,0]
	v_pk_mul_f32 v[32:33], v[156:157], v[16:17] op_sel_hi:[1,0]
	v_pk_mul_f32 v[16:17], v[154:155], v[16:17] op_sel_hi:[1,0]
	v_pk_mul_f32 v[14:15], v[14:15], v[22:23]
	v_pk_mul_f32 v[12:13], v[12:13], v[20:21]
	v_pk_mul_f32 v[10:11], v[10:11], v[26:27]
	v_pk_mul_f32 v[8:9], v[8:9], v[24:25]
	v_pk_mul_f32 v[6:7], v[6:7], v[30:31]
	v_pk_mul_f32 v[4:5], v[4:5], v[28:29]
	v_pk_mul_f32 v[2:3], v[2:3], v[16:17]
	v_pk_mul_f32 v[0:1], v[0:1], v[32:33]
	global_store_dwordx4 v[18:19], v[12:15], off
	global_store_dwordx4 v[18:19], v[8:11], off offset:64
	global_store_dwordx4 v[18:19], v[4:7], off offset:512
	global_store_dwordx4 v[18:19], v[0:3], off offset:576
	s_branch .LBB0_563
